# up-GEMM K-loop: LDS-DMA pieces rebalanced 4+4 per load segment (A[b][0] half-tile staged one super-phase later), vmcnt 8/6
# baseline (speedup 1.0000x reference)
; #define PG8_STAGE(bufoff, gbase, voff) do { _Pragma("unroll") for (int _i = 0; _i < 2; ++_i) \
;         __builtin_amdgcn_global_load_lds((const unsigned*)((const char*)(gbase) + (voff)[_i]), (PG8_LAS unsigned*)(lds + (bufoff) + ldsw + _i * 8192), 16, 0, 0); } while (0)
; #define PG8_LDA(dst, b, h) do { _Pragma("unroll") for (int m = 0; m < 4; ++m) _Pragma("unroll") for (int k = 0; k < 2; ++k) dst[m][k] = *(const PG8_LAS bf16x8*)(lds + PG8_SA(b, h) + aoff + m * 2048 + k * 1024); } while (0)
; #define PG8_LDB(dst, b, h) do { _Pragma("unroll") for (int n = 0; n < 2; ++n) _Pragma("unroll") for (int k = 0; k < 2; ++k) dst[n][k] = *(const PG8_LAS bf16x8*)(lds + PG8_SB(b, h) + boff + n * 2048 + k * 1024); } while (0)
; #define PG8_MMA(ai, bj, At, Bt) do { __builtin_amdgcn_s_setprio(1); _Pragma("unroll") for (int m = 0; m < 4; ++m) _Pragma("unroll") for (int n = 0; n < 2; ++n) _Pragma("unroll") for (int k = 0; k < 2; ++k) \
;         acc[ai][bj][m][n] = __builtin_amdgcn_mfma_f32_16x16x32_bf16(Bt[n][k], At[m][k], acc[ai][bj][m][n], 0, 0, 0); __builtin_amdgcn_s_setprio(0); } while (0)
; #define PG8_WAIT_V(n) asm volatile("s_waitcnt vmcnt(" #n ")" ::: "memory")
; #define PG8_WAIT_L(n) asm volatile("s_waitcnt lgkmcnt(" #n ")" ::: "memory")
; #define PG8_BAR __builtin_amdgcn_s_barrier()
; template <class Epi, class Sched, bool ALIGN_EPI = false, bool SP2 = false>
; __device__ __forceinline__ void gemm_phase(PG8_LAS unsigned char* lds, const Gemm g, const Sched& S, const Epi& E) {
;     ...
;         const bool has_next = S.next(ui + 1, nxt);
;         const char* nA = has_next ? (const char*)g.A + (size_t)nxt.pm * tstep : cA; const char* nB = has_next ? (const char*)g.Bt + (size_t)nxt.pn * tstep : cB;
;         for (int t = 0; t < nt; t += 2) {
;             const bool last = (t == nt - 2);
;             const char* a1 = cA + (size_t)(t + 1) * kstep;
;             const char* a2 = last ? nA : cA + (size_t)(t + 2) * kstep; const char* b2 = last ? nB : cB + (size_t)(t + 2) * kstep;
;             const char* a3 = a2 + kstep; const char* b3 = b2 + kstep;
;             if (last && has_next) S.a_ready(nxt);
;             if constexpr (SP2) {
;             PG8_LDB(B0, 0, 0); PG8_LDB(B1, 0, 1); PG8_SCHED; PG8_LDA(At, 0, 0); PG8_STAGE(PG8_SA(1, 1), a1 + hstep, voffA);
;             PG8_WAIT_V(8); PG8_WAIT_L(0); PG8_BAR; PG8_MMA(0, 0, At, B0); PG8_MMA(0, 1, At, B1); PG8_BAR; PG8_SCHED;
.LBB0_1700:
	s_ashr_i32 s49, s48, 31
	s_lshl_b64 s[10:11], s[48:49], 20
	v_readlane_b32 s0, v244, 38
	s_add_u32 s40, s0, s10
	v_readlane_b32 s0, v244, 22
	s_addc_u32 s41, s0, s11
	s_and_b64 s[10:11], s[4:5], exec
	s_cselect_b32 s7, s41, s75
	s_cselect_b32 s12, s40, s74
	s_ashr_i32 s35, s34, 31
	s_lshl_b64 s[10:11], s[34:35], 20
	s_add_u32 s2, s92, s10
	s_addc_u32 s3, s51, s11
	s_and_b64 s[10:11], s[4:5], exec
	s_cselect_b32 s13, s3, s77
	s_cselect_b32 s16, s2, s76
	s_add_u32 s0, s74, 0x80080
	s_addc_u32 s1, s75, 0
	s_add_u32 s37, s76, 0x100
	v_mov_b32_e32 v0, 0
	s_addc_u32 s71, s77, 0
	s_mov_b32 s73, -2
	v_mov_b32_e32 v1, v0
	v_mov_b32_e32 v2, v0
	v_mov_b32_e32 v3, v0
	v_mov_b32_e32 v16, v0
	v_mov_b32_e32 v17, v0
	v_mov_b32_e32 v18, v0
	v_mov_b32_e32 v19, v0
	v_mov_b32_e32 v4, v0
	v_mov_b32_e32 v5, v0
	v_mov_b32_e32 v6, v0
	v_mov_b32_e32 v7, v0
	v_mov_b32_e32 v20, v0
	v_mov_b32_e32 v21, v0
	v_mov_b32_e32 v22, v0
	v_mov_b32_e32 v23, v0
	v_mov_b32_e32 v8, v0
	v_mov_b32_e32 v9, v0
	v_mov_b32_e32 v10, v0
	v_mov_b32_e32 v11, v0
	v_mov_b32_e32 v24, v0
	v_mov_b32_e32 v25, v0
	v_mov_b32_e32 v26, v0
	v_mov_b32_e32 v27, v0
	v_mov_b32_e32 v12, v0
	v_mov_b32_e32 v13, v0
	v_mov_b32_e32 v14, v0
	v_mov_b32_e32 v15, v0
	v_mov_b32_e32 v28, v0
	v_mov_b32_e32 v29, v0
	v_mov_b32_e32 v30, v0
	v_mov_b32_e32 v31, v0
	v_mov_b32_e32 v32, v0
	v_mov_b32_e32 v33, v0
	v_mov_b32_e32 v34, v0
	v_mov_b32_e32 v35, v0
	v_mov_b32_e32 v48, v0
	v_mov_b32_e32 v49, v0
	v_mov_b32_e32 v50, v0
	v_mov_b32_e32 v51, v0
	v_mov_b32_e32 v36, v0
	v_mov_b32_e32 v37, v0
	v_mov_b32_e32 v38, v0
	v_mov_b32_e32 v39, v0
	v_mov_b32_e32 v52, v0
	v_mov_b32_e32 v53, v0
	v_mov_b32_e32 v54, v0
	v_mov_b32_e32 v55, v0
	v_mov_b32_e32 v40, v0
	v_mov_b32_e32 v41, v0
	v_mov_b32_e32 v42, v0
	v_mov_b32_e32 v43, v0
	v_mov_b32_e32 v56, v0
	v_mov_b32_e32 v57, v0
	v_mov_b32_e32 v58, v0
	v_mov_b32_e32 v59, v0
	v_mov_b32_e32 v44, v0
	v_mov_b32_e32 v45, v0
	v_mov_b32_e32 v46, v0
	v_mov_b32_e32 v47, v0
	v_mov_b32_e32 v60, v0
	v_mov_b32_e32 v61, v0
	v_mov_b32_e32 v62, v0
	v_mov_b32_e32 v63, v0
	v_mov_b32_e32 v64, v0
	v_mov_b32_e32 v65, v0
	v_mov_b32_e32 v66, v0
	v_mov_b32_e32 v67, v0
	v_mov_b32_e32 v84, v0
	v_mov_b32_e32 v85, v0
	v_mov_b32_e32 v86, v0
	v_mov_b32_e32 v87, v0
	v_mov_b32_e32 v68, v0
	v_mov_b32_e32 v69, v0
	v_mov_b32_e32 v70, v0
	v_mov_b32_e32 v71, v0
	v_mov_b32_e32 v88, v0
	v_mov_b32_e32 v89, v0
	v_mov_b32_e32 v90, v0
	v_mov_b32_e32 v91, v0
	v_mov_b32_e32 v72, v0
	v_mov_b32_e32 v73, v0
	v_mov_b32_e32 v74, v0
	v_mov_b32_e32 v75, v0
	v_mov_b32_e32 v96, v0
	v_mov_b32_e32 v97, v0
	v_mov_b32_e32 v98, v0
	v_mov_b32_e32 v99, v0
	v_mov_b32_e32 v76, v0
	v_mov_b32_e32 v77, v0
	v_mov_b32_e32 v78, v0
	v_mov_b32_e32 v79, v0
	v_mov_b32_e32 v100, v0
	v_mov_b32_e32 v101, v0
	v_mov_b32_e32 v102, v0
	v_mov_b32_e32 v103, v0
	v_mov_b32_e32 v92, v0
	v_mov_b32_e32 v93, v0
	v_mov_b32_e32 v94, v0
	v_mov_b32_e32 v95, v0
	v_mov_b32_e32 v80, v0
	v_mov_b32_e32 v81, v0
	v_mov_b32_e32 v82, v0
	v_mov_b32_e32 v83, v0
	v_mov_b32_e32 v108, v0
	v_mov_b32_e32 v109, v0
	v_mov_b32_e32 v110, v0
	v_mov_b32_e32 v111, v0
	v_mov_b32_e32 v104, v0
	v_mov_b32_e32 v105, v0
	v_mov_b32_e32 v106, v0
	v_mov_b32_e32 v107, v0
	v_mov_b32_e32 v112, v0
	v_mov_b32_e32 v113, v0
	v_mov_b32_e32 v114, v0
	v_mov_b32_e32 v115, v0
	v_mov_b32_e32 v120, v0
	v_mov_b32_e32 v121, v0
	v_mov_b32_e32 v122, v0
	v_mov_b32_e32 v123, v0
	v_mov_b32_e32 v116, v0
	v_mov_b32_e32 v117, v0
	v_mov_b32_e32 v118, v0
	v_mov_b32_e32 v119, v0
	v_mov_b32_e32 v124, v0
	v_mov_b32_e32 v125, v0
	v_mov_b32_e32 v126, v0
	v_mov_b32_e32 v127, v0
	v_lshl_add_u64 v[226:227], s[74:75], 0, v[146:147]
	v_lshl_add_u64 v[228:229], s[74:75], 0, v[150:151]
.LBB0_1701:
	ds_read_b128 v[128:131], v220
	ds_read_b128 v[132:135], v220 offset:1024
	ds_read_b128 v[136:139], v220 offset:2048
	ds_read_b128 v[140:143], v220 offset:3072
	ds_read_b128 v[164:167], v221
	ds_read_b128 v[168:171], v221 offset:1024
	ds_read_b128 v[172:175], v221 offset:2048
	ds_read_b128 v[176:179], v221 offset:3072
	s_add_u32 s8, s0, 0xfff80080
	s_addc_u32 s9, s1, -1
	s_cmp_eq_u32 s73, 28
	s_cselect_b32 s11, s7, s9
	s_cselect_b32 s10, s12, s8
	s_cselect_b32 s9, s13, s71
	s_cselect_b32 s8, s16, s37
	v_lshl_add_u64 v[212:213], v[226:227], 0, s[46:47]
	s_mov_b32 m0, s84
	s_nop 0
	global_load_lds_dwordx4 v[212:213], off
	v_lshl_add_u64 v[212:213], v[228:229], 0, s[46:47]
	s_mov_b32 m0, s85
	s_nop 0
	global_load_lds_dwordx4 v[212:213], off
	v_lshl_add_u64 v[212:213], s[0:1], 0, v[156:157]
	s_add_i32 m0, s61, 0xc000
	ds_read_b128 v[180:183], v222
	ds_read_b128 v[184:187], v222 offset:1024
	ds_read_b128 v[188:191], v222 offset:2048
	ds_read_b128 v[192:195], v222 offset:3072
	ds_read_b128 v[196:199], v222 offset:4096
	ds_read_b128 v[200:203], v222 offset:5120
	ds_read_b128 v[204:207], v222 offset:6144
	ds_read_b128 v[208:211], v222 offset:7168
	global_load_lds_dwordx4 v[212:213], off
	v_lshl_add_u64 v[212:213], s[0:1], 0, v[158:159]
	s_add_i32 m0, s61, 0xe000
	s_nop 0
	global_load_lds_dwordx4 v[212:213], off
	s_waitcnt vmcnt(8)
	s_waitcnt lgkmcnt(0)
	s_barrier
; #define PG8_STAGE(bufoff, gbase, voff) do { _Pragma("unroll") for (int _i = 0; _i < 2; ++_i) \
;         __builtin_amdgcn_global_load_lds((const unsigned*)((const char*)(gbase) + (voff)[_i]), (PG8_LAS unsigned*)(lds + (bufoff) + ldsw + _i * 8192), 16, 0, 0); } while (0)
; #define PG8_LDA(dst, b, h) do { _Pragma("unroll") for (int m = 0; m < 4; ++m) _Pragma("unroll") for (int k = 0; k < 2; ++k) dst[m][k] = *(const PG8_LAS bf16x8*)(lds + PG8_SA(b, h) + aoff + m * 2048 + k * 1024); } while (0)
; #define PG8_MMA(ai, bj, At, Bt) do { __builtin_amdgcn_s_setprio(1); _Pragma("unroll") for (int m = 0; m < 4; ++m) _Pragma("unroll") for (int n = 0; n < 2; ++n) _Pragma("unroll") for (int k = 0; k < 2; ++k) \
;         acc[ai][bj][m][n] = __builtin_amdgcn_mfma_f32_16x16x32_bf16(Bt[n][k], At[m][k], acc[ai][bj][m][n], 0, 0, 0); __builtin_amdgcn_s_setprio(0); } while (0)
; #define PG8_WAIT_V(n) asm volatile("s_waitcnt vmcnt(" #n ")" ::: "memory")
; #define PG8_WAIT_L(n) asm volatile("s_waitcnt lgkmcnt(" #n ")" ::: "memory")
; #define PG8_BAR __builtin_amdgcn_s_barrier()
; #define PG8_SCHED __builtin_amdgcn_sched_barrier(0)
; template <class Epi, class Sched, bool ALIGN_EPI = false, bool SP2 = false>
; __device__ __forceinline__ void gemm_phase(PG8_LAS unsigned char* lds, const Gemm g, const Sched& S, const Epi& E) {
;     ...
;             PG8_WAIT_V(8); PG8_WAIT_L(0); PG8_BAR; PG8_MMA(0, 0, At, B0); PG8_MMA(0, 1, At, B1); PG8_BAR; PG8_SCHED;
;             PG8_LDA(At, 0, 1); PG8_STAGE(PG8_SB(0, 0), b2, voffB); PG8_STAGE(PG8_SB(0, 1), b2 + hstep, voffB); PG8_STAGE(PG8_SA(0, 0), a2, voffA);
;             PG8_WAIT_V(8); PG8_WAIT_L(0); PG8_BAR; PG8_MMA(1, 0, At, B0); PG8_MMA(1, 1, At, B1); PG8_BAR; PG8_SCHED;
	s_setprio 1
	s_waitcnt lgkmcnt(0)
	v_mfma_f32_16x16x32_bf16 v[124:127], v[128:131], v[180:183], v[124:127]
	v_mfma_f32_16x16x32_bf16 v[116:119], v[136:139], v[180:183], v[116:119]
	v_mfma_f32_16x16x32_bf16 v[120:123], v[128:131], v[188:191], v[120:123]
	v_mfma_f32_16x16x32_bf16 v[112:115], v[136:139], v[188:191], v[112:115]
	v_mfma_f32_16x16x32_bf16 v[104:107], v[128:131], v[196:199], v[104:107]
	v_mfma_f32_16x16x32_bf16 v[108:111], v[136:139], v[196:199], v[108:111]
	v_mfma_f32_16x16x32_bf16 v[80:83], v[128:131], v[204:207], v[80:83]
	v_mfma_f32_16x16x32_bf16 v[92:95], v[136:139], v[204:207], v[92:95]
	v_mfma_f32_16x16x32_bf16 v[124:127], v[132:135], v[184:187], v[124:127]
	v_mfma_f32_16x16x32_bf16 v[116:119], v[140:143], v[184:187], v[116:119]
	v_mfma_f32_16x16x32_bf16 v[120:123], v[132:135], v[192:195], v[120:123]
	v_mfma_f32_16x16x32_bf16 v[112:115], v[140:143], v[192:195], v[112:115]
	v_mfma_f32_16x16x32_bf16 v[104:107], v[132:135], v[200:203], v[104:107]
	v_mfma_f32_16x16x32_bf16 v[108:111], v[140:143], v[200:203], v[108:111]
	v_mfma_f32_16x16x32_bf16 v[80:83], v[132:135], v[208:211], v[80:83]
	v_mfma_f32_16x16x32_bf16 v[92:95], v[140:143], v[208:211], v[92:95]
	s_setprio 0
	s_setprio 1
	v_mfma_f32_16x16x32_bf16 v[100:103], v[164:167], v[180:183], v[100:103]
	v_mfma_f32_16x16x32_bf16 v[76:79], v[172:175], v[180:183], v[76:79]
	v_mfma_f32_16x16x32_bf16 v[96:99], v[164:167], v[188:191], v[96:99]
	v_mfma_f32_16x16x32_bf16 v[72:75], v[172:175], v[188:191], v[72:75]
	v_mfma_f32_16x16x32_bf16 v[88:91], v[164:167], v[196:199], v[88:91]
	v_mfma_f32_16x16x32_bf16 v[68:71], v[172:175], v[196:199], v[68:71]
	v_mfma_f32_16x16x32_bf16 v[84:87], v[164:167], v[204:207], v[84:87]
	v_mfma_f32_16x16x32_bf16 v[64:67], v[172:175], v[204:207], v[64:67]
	v_mfma_f32_16x16x32_bf16 v[100:103], v[168:171], v[184:187], v[100:103]
	v_mfma_f32_16x16x32_bf16 v[76:79], v[176:179], v[184:187], v[76:79]
	v_mfma_f32_16x16x32_bf16 v[96:99], v[168:171], v[192:195], v[96:99]
	v_mfma_f32_16x16x32_bf16 v[72:75], v[176:179], v[192:195], v[72:75]
	v_mfma_f32_16x16x32_bf16 v[88:91], v[168:171], v[200:203], v[88:91]
	v_mfma_f32_16x16x32_bf16 v[68:71], v[176:179], v[200:203], v[68:71]
	v_mfma_f32_16x16x32_bf16 v[84:87], v[168:171], v[208:211], v[84:87]
	v_mfma_f32_16x16x32_bf16 v[64:67], v[176:179], v[208:211], v[64:67]
	s_setprio 0
	s_barrier
	s_add_i32 s79, s15, s59
	v_lshl_add_u64 v[212:213], s[8:9], 0, v[148:149]
	s_mov_b32 m0, s79
	ds_read_b128 v[180:183], v222 offset:16384
	ds_read_b128 v[184:187], v222 offset:17408
	ds_read_b128 v[188:191], v222 offset:18432
	ds_read_b128 v[192:195], v222 offset:19456
	ds_read_b128 v[196:199], v222 offset:20480
	ds_read_b128 v[200:203], v222 offset:21504
	ds_read_b128 v[204:207], v222 offset:22528
	ds_read_b128 v[208:211], v222 offset:23552
	global_load_lds_dwordx4 v[212:213], off
	s_add_i32 m0, s79, 0x2000
	s_add_u32 vcc_lo, s8, 0x80000
	v_lshl_add_u64 v[214:215], s[8:9], 0, v[152:153]
	s_addc_u32 vcc_hi, s9, 0
	s_add_i32 s79, s87, s59
	global_load_lds_dwordx4 v[214:215], off
	v_lshl_add_u64 v[226:227], vcc, 0, v[148:149]
	s_mov_b32 m0, s79
	v_lshl_add_u64 v[228:229], s[10:11], 0, v[150:151]
	global_load_lds_dwordx4 v[226:227], off
	v_lshl_add_u64 v[226:227], vcc, 0, v[152:153]
	s_add_i32 m0, s79, 0x2000
	s_nop 0
	global_load_lds_dwordx4 v[226:227], off
	v_lshl_add_u64 v[226:227], s[10:11], 0, v[146:147]
	s_waitcnt vmcnt(6)
	s_waitcnt lgkmcnt(0)
	s_barrier
	s_setprio 1
	s_waitcnt lgkmcnt(0)
	v_mfma_f32_16x16x32_bf16 v[60:63], v[128:131], v[180:183], v[60:63]
	v_mfma_f32_16x16x32_bf16 v[44:47], v[136:139], v[180:183], v[44:47]
	v_mfma_f32_16x16x32_bf16 v[56:59], v[128:131], v[188:191], v[56:59]
	v_mfma_f32_16x16x32_bf16 v[40:43], v[136:139], v[188:191], v[40:43]
	v_mfma_f32_16x16x32_bf16 v[52:55], v[128:131], v[196:199], v[52:55]
	v_mfma_f32_16x16x32_bf16 v[36:39], v[136:139], v[196:199], v[36:39]
	v_mfma_f32_16x16x32_bf16 v[48:51], v[128:131], v[204:207], v[48:51]
	v_mfma_f32_16x16x32_bf16 v[32:35], v[136:139], v[204:207], v[32:35]
	v_mfma_f32_16x16x32_bf16 v[60:63], v[132:135], v[184:187], v[60:63]
	v_mfma_f32_16x16x32_bf16 v[44:47], v[140:143], v[184:187], v[44:47]
	v_mfma_f32_16x16x32_bf16 v[56:59], v[132:135], v[192:195], v[56:59]
	v_mfma_f32_16x16x32_bf16 v[40:43], v[140:143], v[192:195], v[40:43]
	v_mfma_f32_16x16x32_bf16 v[52:55], v[132:135], v[200:203], v[52:55]
	v_mfma_f32_16x16x32_bf16 v[36:39], v[140:143], v[200:203], v[36:39]
	v_mfma_f32_16x16x32_bf16 v[48:51], v[132:135], v[208:211], v[48:51]
	v_mfma_f32_16x16x32_bf16 v[32:35], v[140:143], v[208:211], v[32:35]
	s_setprio 0
	s_setprio 1
	v_mfma_f32_16x16x32_bf16 v[28:31], v[164:167], v[180:183], v[28:31]
	v_mfma_f32_16x16x32_bf16 v[12:15], v[172:175], v[180:183], v[12:15]
	v_mfma_f32_16x16x32_bf16 v[24:27], v[164:167], v[188:191], v[24:27]
	v_mfma_f32_16x16x32_bf16 v[8:11], v[172:175], v[188:191], v[8:11]
	v_mfma_f32_16x16x32_bf16 v[20:23], v[164:167], v[196:199], v[20:23]
	v_mfma_f32_16x16x32_bf16 v[4:7], v[172:175], v[196:199], v[4:7]
	v_mfma_f32_16x16x32_bf16 v[16:19], v[164:167], v[204:207], v[16:19]
	v_mfma_f32_16x16x32_bf16 v[0:3], v[172:175], v[204:207], v[0:3]
	v_mfma_f32_16x16x32_bf16 v[28:31], v[168:171], v[184:187], v[28:31]
	v_mfma_f32_16x16x32_bf16 v[12:15], v[176:179], v[184:187], v[12:15]
	v_mfma_f32_16x16x32_bf16 v[24:27], v[168:171], v[192:195], v[24:27]
	v_mfma_f32_16x16x32_bf16 v[8:11], v[176:179], v[192:195], v[8:11]
	v_mfma_f32_16x16x32_bf16 v[20:23], v[168:171], v[200:203], v[20:23]
	v_mfma_f32_16x16x32_bf16 v[4:7], v[176:179], v[200:203], v[4:7]
	v_mfma_f32_16x16x32_bf16 v[16:19], v[168:171], v[208:211], v[16:19]
	v_mfma_f32_16x16x32_bf16 v[0:3], v[176:179], v[208:211], v[0:3]
	s_setprio 0
	s_barrier
; #define PG8_STAGE(bufoff, gbase, voff) do { _Pragma("unroll") for (int _i = 0; _i < 2; ++_i) \
;         __builtin_amdgcn_global_load_lds((const unsigned*)((const char*)(gbase) + (voff)[_i]), (PG8_LAS unsigned*)(lds + (bufoff) + ldsw + _i * 8192), 16, 0, 0); } while (0)
; #define PG8_LDA(dst, b, h) do { _Pragma("unroll") for (int m = 0; m < 4; ++m) _Pragma("unroll") for (int k = 0; k < 2; ++k) dst[m][k] = *(const PG8_LAS bf16x8*)(lds + PG8_SA(b, h) + aoff + m * 2048 + k * 1024); } while (0)
; #define PG8_LDB(dst, b, h) do { _Pragma("unroll") for (int n = 0; n < 2; ++n) _Pragma("unroll") for (int k = 0; k < 2; ++k) dst[n][k] = *(const PG8_LAS bf16x8*)(lds + PG8_SB(b, h) + boff + n * 2048 + k * 1024); } while (0)
; #define PG8_MMA(ai, bj, At, Bt) do { __builtin_amdgcn_s_setprio(1); _Pragma("unroll") for (int m = 0; m < 4; ++m) _Pragma("unroll") for (int n = 0; n < 2; ++n) _Pragma("unroll") for (int k = 0; k < 2; ++k) \
;         acc[ai][bj][m][n] = __builtin_amdgcn_mfma_f32_16x16x32_bf16(Bt[n][k], At[m][k], acc[ai][bj][m][n], 0, 0, 0); __builtin_amdgcn_s_setprio(0); } while (0)
; #define PG8_WAIT_V(n) asm volatile("s_waitcnt vmcnt(" #n ")" ::: "memory")
; #define PG8_WAIT_L(n) asm volatile("s_waitcnt lgkmcnt(" #n ")" ::: "memory")
; #define PG8_BAR __builtin_amdgcn_s_barrier()
; #define PG8_SCHED __builtin_amdgcn_sched_barrier(0)
; template <class Epi, class Sched, bool ALIGN_EPI = false, bool SP2 = false>
; __device__ __forceinline__ void gemm_phase(PG8_LAS unsigned char* lds, const Gemm g, const Sched& S, const Epi& E) {
;     ...
;             PG8_WAIT_V(8); PG8_WAIT_L(0); PG8_BAR; PG8_MMA(1, 0, At, B0); PG8_MMA(1, 1, At, B1); PG8_BAR; PG8_SCHED;
;             PG8_LDB(B0, 1, 0); PG8_LDB(B1, 1, 1); PG8_SCHED; PG8_LDA(At, 1, 0); PG8_STAGE(PG8_SA(0, 1), a2 + hstep, voffA);
;             PG8_WAIT_V(8); PG8_WAIT_L(0); PG8_BAR; PG8_MMA(0, 0, At, B0); PG8_MMA(0, 1, At, B1); PG8_BAR; PG8_SCHED;
	s_add_i32 s79, 0, 0x18000
	s_add_i32 vcc_lo, 0, 0x1c000
	v_add_u32_e32 v140, s79, v219
	v_add_u32_e32 v154, vcc_lo, v219
	ds_read_b128 v[128:131], v140
	ds_read_b128 v[132:135], v140 offset:1024
	ds_read_b128 v[136:139], v140 offset:2048
	ds_read_b128 v[140:143], v140 offset:3072
	ds_read_b128 v[164:167], v154
	ds_read_b128 v[168:171], v154 offset:1024
	ds_read_b128 v[172:175], v154 offset:2048
	ds_read_b128 v[176:179], v154 offset:3072
	s_add_u32 s10, s10, 0x80000
	s_addc_u32 s11, s11, 0
	s_mov_b32 m0, s61
	s_nop 0
	global_load_lds_dwordx4 v[226:227], off
	s_mov_b32 m0, s63
	s_nop 0
	global_load_lds_dwordx4 v[228:229], off
	s_mov_b32 m0, s65
	v_lshl_add_u64 v[230:231], s[10:11], 0, v[146:147]
	ds_read_b128 v[180:183], v222 offset:32768
	ds_read_b128 v[184:187], v222 offset:33792
	ds_read_b128 v[188:191], v222 offset:34816
	ds_read_b128 v[192:195], v222 offset:35840
	ds_read_b128 v[196:199], v222 offset:36864
	ds_read_b128 v[200:203], v222 offset:37888
	ds_read_b128 v[204:207], v222 offset:38912
	ds_read_b128 v[208:211], v222 offset:39936
	global_load_lds_dwordx4 v[230:231], off
	v_lshl_add_u64 v[230:231], s[10:11], 0, v[150:151]
	s_mov_b32 m0, s67
	s_nop 0
	global_load_lds_dwordx4 v[230:231], off
	s_waitcnt vmcnt(8)
	s_waitcnt lgkmcnt(0)
	s_barrier
	s_setprio 1
	s_waitcnt lgkmcnt(0)
	v_mfma_f32_16x16x32_bf16 v[124:127], v[128:131], v[180:183], v[124:127]
	v_mfma_f32_16x16x32_bf16 v[116:119], v[136:139], v[180:183], v[116:119]
	v_mfma_f32_16x16x32_bf16 v[120:123], v[128:131], v[188:191], v[120:123]
	v_mfma_f32_16x16x32_bf16 v[112:115], v[136:139], v[188:191], v[112:115]
	v_mfma_f32_16x16x32_bf16 v[104:107], v[128:131], v[196:199], v[104:107]
	v_mfma_f32_16x16x32_bf16 v[108:111], v[136:139], v[196:199], v[108:111]
	v_mfma_f32_16x16x32_bf16 v[80:83], v[128:131], v[204:207], v[80:83]
	v_mfma_f32_16x16x32_bf16 v[92:95], v[136:139], v[204:207], v[92:95]
	v_mfma_f32_16x16x32_bf16 v[124:127], v[132:135], v[184:187], v[124:127]
	v_mfma_f32_16x16x32_bf16 v[116:119], v[140:143], v[184:187], v[116:119]
	v_mfma_f32_16x16x32_bf16 v[120:123], v[132:135], v[192:195], v[120:123]
	v_mfma_f32_16x16x32_bf16 v[112:115], v[140:143], v[192:195], v[112:115]
	v_mfma_f32_16x16x32_bf16 v[104:107], v[132:135], v[200:203], v[104:107]
	v_mfma_f32_16x16x32_bf16 v[108:111], v[140:143], v[200:203], v[108:111]
	v_mfma_f32_16x16x32_bf16 v[80:83], v[132:135], v[208:211], v[80:83]
	v_mfma_f32_16x16x32_bf16 v[92:95], v[140:143], v[208:211], v[92:95]
	s_setprio 0
	s_setprio 1
	v_mfma_f32_16x16x32_bf16 v[100:103], v[164:167], v[180:183], v[100:103]
	v_mfma_f32_16x16x32_bf16 v[76:79], v[172:175], v[180:183], v[76:79]
	v_mfma_f32_16x16x32_bf16 v[96:99], v[164:167], v[188:191], v[96:99]
	v_mfma_f32_16x16x32_bf16 v[72:75], v[172:175], v[188:191], v[72:75]
	v_mfma_f32_16x16x32_bf16 v[88:91], v[164:167], v[196:199], v[88:91]
	v_mfma_f32_16x16x32_bf16 v[68:71], v[172:175], v[196:199], v[68:71]
	v_mfma_f32_16x16x32_bf16 v[84:87], v[164:167], v[204:207], v[84:87]
	v_mfma_f32_16x16x32_bf16 v[64:67], v[172:175], v[204:207], v[64:67]
	v_mfma_f32_16x16x32_bf16 v[100:103], v[168:171], v[184:187], v[100:103]
	v_mfma_f32_16x16x32_bf16 v[76:79], v[176:179], v[184:187], v[76:79]
	v_mfma_f32_16x16x32_bf16 v[96:99], v[168:171], v[192:195], v[96:99]
	v_mfma_f32_16x16x32_bf16 v[72:75], v[176:179], v[192:195], v[72:75]
	v_mfma_f32_16x16x32_bf16 v[88:91], v[168:171], v[200:203], v[88:91]
	v_mfma_f32_16x16x32_bf16 v[68:71], v[176:179], v[200:203], v[68:71]
	v_mfma_f32_16x16x32_bf16 v[84:87], v[168:171], v[208:211], v[84:87]
	v_mfma_f32_16x16x32_bf16 v[64:67], v[176:179], v[208:211], v[64:67]
	s_setprio 0
	s_barrier
; #define PG8_STAGE(bufoff, gbase, voff) do { _Pragma("unroll") for (int _i = 0; _i < 2; ++_i) \
;         __builtin_amdgcn_global_load_lds((const unsigned*)((const char*)(gbase) + (voff)[_i]), (PG8_LAS unsigned*)(lds + (bufoff) + ldsw + _i * 8192), 16, 0, 0); } while (0)
; #define PG8_LDA(dst, b, h) do { _Pragma("unroll") for (int m = 0; m < 4; ++m) _Pragma("unroll") for (int k = 0; k < 2; ++k) dst[m][k] = *(const PG8_LAS bf16x8*)(lds + PG8_SA(b, h) + aoff + m * 2048 + k * 1024); } while (0)
; #define PG8_MMA(ai, bj, At, Bt) do { __builtin_amdgcn_s_setprio(1); _Pragma("unroll") for (int m = 0; m < 4; ++m) _Pragma("unroll") for (int n = 0; n < 2; ++n) _Pragma("unroll") for (int k = 0; k < 2; ++k) \
;         acc[ai][bj][m][n] = __builtin_amdgcn_mfma_f32_16x16x32_bf16(Bt[n][k], At[m][k], acc[ai][bj][m][n], 0, 0, 0); __builtin_amdgcn_s_setprio(0); } while (0)
; #define PG8_WAIT_V(n) asm volatile("s_waitcnt vmcnt(" #n ")" ::: "memory")
; #define PG8_WAIT_L(n) asm volatile("s_waitcnt lgkmcnt(" #n ")" ::: "memory")
; #define PG8_BAR __builtin_amdgcn_s_barrier()
; #define PG8_SCHED __builtin_amdgcn_sched_barrier(0)
; template <class Epi, class Sched, bool ALIGN_EPI = false, bool SP2 = false>
; __device__ __forceinline__ void gemm_phase(PG8_LAS unsigned char* lds, const Gemm g, const Sched& S, const Epi& E) {
;     ...
;             PG8_LDA(At, 1, 1); PG8_STAGE(PG8_SB(1, 0), b3, voffB); PG8_STAGE(PG8_SB(1, 1), b3 + hstep, voffB); PG8_STAGE(PG8_SA(1, 0), a3, voffA);
;             PG8_WAIT_V(8); PG8_WAIT_L(0); PG8_BAR; PG8_MMA(1, 0, At, B0); PG8_MMA(1, 1, At, B1); PG8_BAR; PG8_SCHED;
	s_add_i32 s10, s79, s59
	v_lshl_add_u64 v[212:213], v[212:213], 0, s[46:47]
	s_mov_b32 m0, s10
	ds_read_b128 v[180:183], v222 offset:49152
	ds_read_b128 v[184:187], v222 offset:50176
	ds_read_b128 v[188:191], v222 offset:51200
	ds_read_b128 v[192:195], v222 offset:52224
	ds_read_b128 v[196:199], v222 offset:53248
	ds_read_b128 v[200:203], v222 offset:54272
	ds_read_b128 v[204:207], v222 offset:55296
	ds_read_b128 v[208:211], v222 offset:56320
	global_load_lds_dwordx4 v[212:213], off
	s_add_i32 m0, s10, 0x2000
	s_add_u32 s8, s8, 0x80080
	v_lshl_add_u64 v[212:213], v[214:215], 0, s[46:47]
	s_addc_u32 s9, s9, 0
	s_add_i32 s10, vcc_lo, s59
	global_load_lds_dwordx4 v[212:213], off
	v_lshl_add_u64 v[212:213], s[8:9], 0, v[148:149]
	s_mov_b32 m0, s10
	s_nop 0
	global_load_lds_dwordx4 v[212:213], off
	v_lshl_add_u64 v[212:213], s[8:9], 0, v[152:153]
	s_add_i32 m0, s10, 0x2000
	s_nop 0
	global_load_lds_dwordx4 v[212:213], off
	s_waitcnt vmcnt(6)
	s_waitcnt lgkmcnt(0)
	s_barrier
	s_setprio 1
	s_waitcnt lgkmcnt(0)
	v_mfma_f32_16x16x32_bf16 v[60:63], v[128:131], v[180:183], v[60:63]
	v_mfma_f32_16x16x32_bf16 v[44:47], v[136:139], v[180:183], v[44:47]
	v_mfma_f32_16x16x32_bf16 v[56:59], v[128:131], v[188:191], v[56:59]
	v_mfma_f32_16x16x32_bf16 v[40:43], v[136:139], v[188:191], v[40:43]
	v_mfma_f32_16x16x32_bf16 v[52:55], v[128:131], v[196:199], v[52:55]
	v_mfma_f32_16x16x32_bf16 v[36:39], v[136:139], v[196:199], v[36:39]
	v_mfma_f32_16x16x32_bf16 v[48:51], v[128:131], v[204:207], v[48:51]
	v_mfma_f32_16x16x32_bf16 v[32:35], v[136:139], v[204:207], v[32:35]
	v_mfma_f32_16x16x32_bf16 v[60:63], v[132:135], v[184:187], v[60:63]
	v_mfma_f32_16x16x32_bf16 v[44:47], v[140:143], v[184:187], v[44:47]
	v_mfma_f32_16x16x32_bf16 v[56:59], v[132:135], v[192:195], v[56:59]
	v_mfma_f32_16x16x32_bf16 v[40:43], v[140:143], v[192:195], v[40:43]
	v_mfma_f32_16x16x32_bf16 v[52:55], v[132:135], v[200:203], v[52:55]
	v_mfma_f32_16x16x32_bf16 v[36:39], v[140:143], v[200:203], v[36:39]
	v_mfma_f32_16x16x32_bf16 v[48:51], v[132:135], v[208:211], v[48:51]
	v_mfma_f32_16x16x32_bf16 v[32:35], v[140:143], v[208:211], v[32:35]
	s_setprio 0
	s_setprio 1
	v_mfma_f32_16x16x32_bf16 v[28:31], v[164:167], v[180:183], v[28:31]
	v_mfma_f32_16x16x32_bf16 v[12:15], v[172:175], v[180:183], v[12:15]
	v_mfma_f32_16x16x32_bf16 v[24:27], v[164:167], v[188:191], v[24:27]
	v_mfma_f32_16x16x32_bf16 v[8:11], v[172:175], v[188:191], v[8:11]
	v_mfma_f32_16x16x32_bf16 v[20:23], v[164:167], v[196:199], v[20:23]
	v_mfma_f32_16x16x32_bf16 v[4:7], v[172:175], v[196:199], v[4:7]
	v_mfma_f32_16x16x32_bf16 v[16:19], v[164:167], v[204:207], v[16:19]
	v_mfma_f32_16x16x32_bf16 v[0:3], v[172:175], v[204:207], v[0:3]
	v_mfma_f32_16x16x32_bf16 v[28:31], v[168:171], v[184:187], v[28:31]
	v_mfma_f32_16x16x32_bf16 v[12:15], v[176:179], v[184:187], v[12:15]
	v_mfma_f32_16x16x32_bf16 v[24:27], v[168:171], v[192:195], v[24:27]
	v_mfma_f32_16x16x32_bf16 v[8:11], v[176:179], v[192:195], v[8:11]
	v_mfma_f32_16x16x32_bf16 v[20:23], v[168:171], v[200:203], v[20:23]
	v_mfma_f32_16x16x32_bf16 v[4:7], v[176:179], v[200:203], v[4:7]
	v_mfma_f32_16x16x32_bf16 v[16:19], v[168:171], v[208:211], v[16:19]
	v_mfma_f32_16x16x32_bf16 v[0:3], v[176:179], v[208:211], v[0:3]
	s_setprio 0
	s_barrier
	s_add_i32 s73, s73, 2
	s_add_u32 s0, s0, 0x100
	s_addc_u32 s1, s1, 0
	s_add_u32 s37, s37, 0x100
	s_addc_u32 s71, s71, 0
	s_cmp_gt_u32 s73, 29
	s_cbranch_scc0 .LBB0_1701
	v_readlane_b32 s0, v244, 56
	v_readlane_b32 s1, v244, 57
	s_and_b64 vcc, exec, s[0:1]
	s_cbranch_vccz .LBB0_1704
	s_barrier
